# diff attention epilogue: the eight output-norm gain loads issued together up front instead of load/wait/store eight times (epilogue de-serialisation)
# speedup vs baseline: 1.0058x; 1.0058x over previous
; DI void diff_mfma_phase(const Args& A, int wave_s, int l, bool need_ctx, LAS unsigned char* lds) {
;     ...
;         for (int it = 0; it < ntiles; ++it) {
;             const int cur = it & 1;
;             if (it + 1 < ntiles) { const int kr0 = (it + 1 < 64 ? kbase0 : kbase1) + (it + 1) * DT_ROWS;
;                 const char* kb_ = (const char*)(C.P + (size_t)kr0 * INW + CC_K + hd * 64);
;                 kreg[0] = *(const v4u*)(kb_ + sgoff); kreg[1] = *(const v4u*)(kb_ + (size_t)64 * INW * 2 + sgoff); }
;             LAS unsigned char* Kb = lds + cur * DT_IMG; LAS unsigned char* Vb = lds + VOFF0 + cur * DV_IMG;
;             LAS unsigned char* kl = Kb + r * KV_PITCH + h * 16;
;             f32x16 Sc;
;             { const bf16x8 kA0 = *(LAS bf16x8*)(kl), kA1 = *(LAS bf16x8*)(kl + 32); Sc = MFMA32(kA0, Qf[0][0], negM); Sc = MFMA32(kA1, Qf[0][1], Sc); }
; #pragma unroll
;             for (int g = 0; g < 8; ++g) {
;                 const int c = g & 1, sub = g >> 1;
;                 bf16x8 kB0, kB1; f32x16 Sn;
;                 if (g < 7) { LAS unsigned char* kp = kl + (32 * ((g + 1) >> 1)) * KV_PITCH + (c ^ 1) * 64; kB0 = *(LAS bf16x8*)(kp); kB1 = *(LAS bf16x8*)(kp + 32); }
;                 if (c == 0) { O[1][0] = MFMA32(Vs[0], Pp0, O[1][0]); O[1][1] = MFMA32(Vs[2], Pp0, O[1][1]); O[1][0] = MFMA32(Vs[1], Pp1, O[1][0]); O[1][1] = MFMA32(Vs[3], Pp1, O[1][1]); }
;                 else        { O[0][0] = MFMA32(Vs[0], Pp0, O[0][0]); O[0][1] = MFMA32(Vs[2], Pp0, O[0][1]); O[0][0] = MFMA32(Vs[1], Pp1, O[0][0]); O[0][1] = MFMA32(Vs[3], Pp1, O[0][1]); }
;                 float t = 0.f;
; #pragma unroll
;                 for (int i = 0; i < 8; ++i) { Sc[i] = __builtin_amdgcn_exp2f(Sc[i]); t += Sc[i]; }
;                 const bf16x8 Pn0 = PACK8(Sc, 0);
;                 __builtin_amdgcn_sched_barrier(0);
;                 if (g < 7) { Sn = MFMA32(kB0, Qf[c ^ 1][0], negM); Sn = MFMA32(kB1, Qf[c ^ 1][1], Sn); }
;                 __builtin_amdgcn_sched_barrier(0);
;                 if (c == 0) { LAS unsigned char* vp = Vb + (32 * sub) * VP + voff; Vs[0] = tr_pairV(vp); Vs[1] = tr_pairV(vp + 16 * VP); Vs[2] = tr_pairV(vp + 64); Vs[3] = tr_pairV(vp + 16 * VP + 64); }
; #pragma unroll
;                 for (int i = 8; i < 16; ++i) { Sc[i] = __builtin_amdgcn_exp2f(Sc[i]); t += Sc[i]; }
;                 if (c == 0) ls0 += t; else ls1 += t;
.LBB0_406:
	s_and_b32 s18, s15, 1
	s_mul_i32 s9, s18, 0x4800
	v_add_u32_e32 v160, s9, v218
	ds_read_b128 v[64:67], v160
	ds_read_b128 v[80:83], v160 offset:32
	s_add_i32 s14, s15, 1
	s_cmp_lt_u32 s15, 63
	s_cselect_b32 s9, s10, s12
	s_ashr_i32 s15, s9, 31
	s_add_u32 s9, s6, s9
	s_addc_u32 s15, s7, s15
	s_mul_hi_u32 s16, s9, 0x1800
	s_waitcnt lgkmcnt(1)
	v_mfma_f32_32x32x16_bf16 v[64:79], v[64:67], v[108:111], 0
	s_mulk_i32 s15, 0x1800
	s_mulk_i32 s9, 0x1800
	s_add_i32 s16, s16, s15
	s_add_u32 s15, s84, s9
	s_addc_u32 s17, s85, s16
	s_lshl_b32 s9, s11, 1
	s_add_u32 s16, s15, s9
	s_addc_u32 s17, s17, 0
	s_waitcnt lgkmcnt(0)
	v_mfma_f32_32x32x16_bf16 v[64:79], v[80:83], v[104:107], v[64:79]
	v_lshl_add_u64 v[80:81], s[16:17], 0, v[138:139]
	v_add_co_u32_e32 v128, vcc, s76, v80
	s_mul_i32 s15, s18, 0x6000
	s_nop 0
	v_addc_co_u32_e32 v129, vcc, 0, v81, vcc
	v_add_co_u32_e32 v132, vcc, s3, v80
	v_mfma_f32_32x32x16_bf16 v[16:31], v[120:123], v[88:91], v[16:31]
	s_nop 0
	v_addc_co_u32_e32 v133, vcc, 0, v81, vcc
	s_nop 2
	v_exp_f32_e32 v130, v64
	v_exp_f32_e32 v134, v65
	v_exp_f32_e32 v164, v66
	v_exp_f32_e32 v184, v67
	v_exp_f32_e32 v186, v68
	v_mfma_f32_32x32x16_bf16 v[0:15], v[124:127], v[88:91], v[0:15]
	global_load_dwordx4 v[120:123], v[128:129], off offset:1024
	global_load_dwordx4 v[124:127], v[132:133], off offset:1024
	v_exp_f32_e32 v188, v69
	v_exp_f32_e32 v190, v70
	v_exp_f32_e32 v192, v71
	v_add_u32_e32 v147, s15, v219
	s_xor_b32 s15, s18, 1
	s_mul_i32 s16, s15, 0x4800
	v_mfma_f32_32x32x16_bf16 v[16:31], v[116:119], v[92:95], v[16:31]
	ds_read_b128 v[80:83], v160 offset:64
	ds_read_b128 v[116:119], v160 offset:96
	s_add_i32 s16, s16, 0
	v_add3_u32 v166, s16, v214, v212
	v_add3_u32 v167, s16, v215, v212
	v_cvt_pk_bf16_f32 v64, v130, v134
	v_cvt_pk_bf16_f32 v65, v164, v184
	v_cvt_pk_bf16_f32 v66, v186, v188
	v_mfma_f32_32x32x16_bf16 v[0:15], v[112:115], v[92:95], v[0:15]
	v_cvt_pk_bf16_f32 v67, v190, v192
	s_waitcnt lgkmcnt(0)
	v_mfma_f32_32x32x16_bf16 v[80:95], v[80:83], v[100:103], 0
	v_mfma_f32_32x32x16_bf16 v[80:95], v[116:119], v[96:99], v[80:95]
	ds_read_b64_tr_b16 v[68:69], v147 offset:36864
	ds_read_b64_tr_b16 v[70:71], v147 offset:38400
	ds_read_b64_tr_b16 v[114:115], v147 offset:38464
	ds_read_b64_tr_b16 v[112:113], v147 offset:36928
	ds_read_b64_tr_b16 v[116:117], v147 offset:39936
	ds_read_b64_tr_b16 v[118:119], v147 offset:41472
	ds_read_b64_tr_b16 v[174:175], v147 offset:41536
	ds_read_b64_tr_b16 v[172:173], v147 offset:40000
	v_exp_f32_e32 v194, v72
	v_exp_f32_e32 v170, v73
	v_exp_f32_e32 v168, v74
	v_exp_f32_e32 v158, v75
	v_exp_f32_e32 v156, v76
	v_exp_f32_e32 v154, v77
	v_exp_f32_e32 v152, v78
	v_exp_f32_e32 v150, v79
	v_cvt_pk_bf16_f32 v72, v194, v170
	v_cvt_pk_bf16_f32 v73, v168, v158
	v_cvt_pk_bf16_f32 v74, v156, v154
	v_cvt_pk_bf16_f32 v75, v152, v150
	s_waitcnt lgkmcnt(6)
	v_mfma_f32_32x32x16_bf16 v[48:63], v[68:71], v[64:67], v[48:63]
	v_exp_f32_e32 v131, v80
	v_exp_f32_e32 v135, v81
	v_exp_f32_e32 v165, v82
	v_exp_f32_e32 v185, v83
	v_exp_f32_e32 v187, v84
	v_exp_f32_e32 v189, v85
	v_exp_f32_e32 v191, v86
	s_waitcnt lgkmcnt(4)
	v_mfma_f32_32x32x16_bf16 v[32:47], v[112:115], v[64:67], v[32:47]
	ds_read_b128 v[64:67], v160 offset:4608
	ds_read_b128 v[176:179], v160 offset:4640
	v_exp_f32_e32 v193, v87
	v_cvt_pk_bf16_f32 v180, v131, v135
	v_cvt_pk_bf16_f32 v181, v165, v185
	v_cvt_pk_bf16_f32 v182, v187, v189
	v_cvt_pk_bf16_f32 v183, v191, v193
	s_waitcnt lgkmcnt(2)
	v_mfma_f32_32x32x16_bf16 v[48:63], v[116:119], v[72:75], v[48:63]
	v_mfma_f32_32x32x16_bf16 v[32:47], v[172:175], v[72:75], v[32:47]
	s_waitcnt lgkmcnt(0)
	v_mfma_f32_32x32x16_bf16 v[72:87], v[64:67], v[108:111], 0
	v_mfma_f32_32x32x16_bf16 v[72:87], v[176:179], v[104:107], v[72:87]
	v_exp_f32_e32 v195, v88
	v_pk_add_f32 v[64:65], v[134:135], v[130:131]
	v_exp_f32_e32 v171, v89
	v_pk_add_f32 v[64:65], v[164:165], v[64:65]
	v_exp_f32_e32 v169, v90
	v_pk_add_f32 v[64:65], v[184:185], v[64:65]
	v_exp_f32_e32 v159, v91
	v_pk_add_f32 v[64:65], v[186:187], v[64:65]
	v_exp_f32_e32 v157, v92
	v_exp_f32_e32 v155, v93
	v_exp_f32_e32 v153, v94
	v_exp_f32_e32 v151, v95
	v_pk_add_f32 v[64:65], v[188:189], v[64:65]
	v_cvt_pk_bf16_f32 v66, v157, v155
	v_pk_add_f32 v[64:65], v[190:191], v[64:65]
	v_cvt_pk_bf16_f32 v67, v153, v151
	v_pk_add_f32 v[64:65], v[192:193], v[64:65]
	s_nop 0
	v_pk_add_f32 v[178:179], v[194:195], v[64:65]
	v_cvt_pk_bf16_f32 v64, v195, v171
	v_cvt_pk_bf16_f32 v65, v169, v159
	v_mfma_f32_32x32x16_bf16 v[16:31], v[68:71], v[180:183], v[16:31]
	ds_read_b128 v[88:91], v160 offset:4672
	ds_read_b128 v[92:95], v160 offset:4704
	v_exp_f32_e32 v130, v72
	v_exp_f32_e32 v134, v73
	v_exp_f32_e32 v164, v74
	v_exp_f32_e32 v208, v75
	v_exp_f32_e32 v210, v76
	v_exp_f32_e32 v222, v77
	v_mfma_f32_32x32x16_bf16 v[0:15], v[112:115], v[180:183], v[0:15]
	v_exp_f32_e32 v224, v78
	v_exp_f32_e32 v226, v79
	v_cvt_pk_bf16_f32 v112, v130, v134
	v_cvt_pk_bf16_f32 v113, v164, v208
	v_cvt_pk_bf16_f32 v114, v210, v222
	v_cvt_pk_bf16_f32 v115, v224, v226
	v_mfma_f32_32x32x16_bf16 v[16:31], v[116:119], v[64:67], v[16:31]
	v_mfma_f32_32x32x16_bf16 v[0:15], v[172:175], v[64:67], v[0:15]
	s_waitcnt lgkmcnt(0)
	v_mfma_f32_32x32x16_bf16 v[64:79], v[88:91], v[100:103], 0
	v_mfma_f32_32x32x16_bf16 v[64:79], v[92:95], v[96:99], v[64:79]
	ds_read_b64_tr_b16 v[116:117], v147 offset:43008
	ds_read_b64_tr_b16 v[118:119], v147 offset:44544
	ds_read_b64_tr_b16 v[194:195], v147 offset:44608
	ds_read_b64_tr_b16 v[192:193], v147 offset:43072
	ds_read_b64_tr_b16 v[196:197], v147 offset:46080
	ds_read_b64_tr_b16 v[198:199], v147 offset:47616
	ds_read_b64_tr_b16 v[202:203], v147 offset:47680
	ds_read_b64_tr_b16 v[200:201], v147 offset:46144
	v_exp_f32_e32 v188, v80
	v_exp_f32_e32 v186, v81
	v_exp_f32_e32 v184, v82
	v_exp_f32_e32 v182, v83
	v_exp_f32_e32 v180, v84
	v_exp_f32_e32 v176, v85
	v_exp_f32_e32 v174, v86
	v_exp_f32_e32 v172, v87
	v_cvt_pk_bf16_f32 v80, v188, v186
	v_cvt_pk_bf16_f32 v81, v184, v182
	v_cvt_pk_bf16_f32 v82, v180, v176
	v_cvt_pk_bf16_f32 v83, v174, v172
	s_waitcnt lgkmcnt(6)
; DI void diff_mfma_phase(const Args& A, int wave_s, int l, bool need_ctx, LAS unsigned char* lds) {
;     ...
;             for (int g = 0; g < 8; ++g) {
;                 const int c = g & 1, sub = g >> 1;
;                 bf16x8 kB0, kB1; f32x16 Sn;
;                 if (g < 7) { LAS unsigned char* kp = kl + (32 * ((g + 1) >> 1)) * KV_PITCH + (c ^ 1) * 64; kB0 = *(LAS bf16x8*)(kp); kB1 = *(LAS bf16x8*)(kp + 32); }
;                 if (c == 0) { O[1][0] = MFMA32(Vs[0], Pp0, O[1][0]); O[1][1] = MFMA32(Vs[2], Pp0, O[1][1]); O[1][0] = MFMA32(Vs[1], Pp1, O[1][0]); O[1][1] = MFMA32(Vs[3], Pp1, O[1][1]); }
;                 else        { O[0][0] = MFMA32(Vs[0], Pp0, O[0][0]); O[0][1] = MFMA32(Vs[2], Pp0, O[0][1]); O[0][0] = MFMA32(Vs[1], Pp1, O[0][0]); O[0][1] = MFMA32(Vs[3], Pp1, O[0][1]); }
;                 float t = 0.f;
; #pragma unroll
;                 for (int i = 0; i < 8; ++i) { Sc[i] = __builtin_amdgcn_exp2f(Sc[i]); t += Sc[i]; }
;                 const bf16x8 Pn0 = PACK8(Sc, 0);
;                 __builtin_amdgcn_sched_barrier(0);
;                 if (g < 7) { Sn = MFMA32(kB0, Qf[c ^ 1][0], negM); Sn = MFMA32(kB1, Qf[c ^ 1][1], Sn); }
;                 __builtin_amdgcn_sched_barrier(0);
;                 if (c == 0) { LAS unsigned char* vp = Vb + (32 * sub) * VP + voff; Vs[0] = tr_pairV(vp); Vs[1] = tr_pairV(vp + 16 * VP); Vs[2] = tr_pairV(vp + 64); Vs[3] = tr_pairV(vp + 16 * VP + 64); }
; #pragma unroll
;                 for (int i = 8; i < 16; ++i) { Sc[i] = __builtin_amdgcn_exp2f(Sc[i]); t += Sc[i]; }
;                 if (c == 0) ls0 += t; else ls1 += t;
;                 Pp0 = Pn0; Pp1 = PACK8(Sc, 1);
;                 if (g < 7) Sc = Sn;
;                 __builtin_amdgcn_sched_barrier(0);
;                 if (g == 3 && it + 1 < ntiles) {
;                     LAS unsigned char* kb2 = lds + (cur ^ 1) * DT_IMG;
;                     *(LAS v4u*)(kb2 + srow * KV_PITCH + sch * 16) = kreg[0]; *(LAS v4u*)(kb2 + (srow + 64) * KV_PITCH + sch * 16) = kreg[1];
;                     const int kr0 = (it + 1 < 64 ? kbase0 : kbase1) + (it + 1) * DT_ROWS;
;                     const char* vb_ = (const char*)(C.P + (size_t)kr0 * INW + CC_V + hd * 64);
;                     kreg[0] = *(const v4u*)(vb_ + sgoff); kreg[1] = *(const v4u*)(vb_ + (size_t)64 * INW * 2 + sgoff);
;                     __builtin_amdgcn_sched_barrier(0);
;                 }
	v_mfma_f32_32x32x16_bf16 v[48:63], v[116:119], v[112:115], v[48:63]
	v_exp_f32_e32 v131, v64
	v_exp_f32_e32 v135, v65
	v_exp_f32_e32 v165, v66
	v_exp_f32_e32 v209, v67
	v_exp_f32_e32 v211, v68
	v_exp_f32_e32 v223, v69
	s_waitcnt lgkmcnt(4)
	v_mfma_f32_32x32x16_bf16 v[32:47], v[192:195], v[112:115], v[32:47]
	v_pk_add_f32 v[64:65], v[134:135], v[130:131]
	ds_read_b128 v[84:87], v160 offset:9216
	ds_read_b128 v[204:207], v160 offset:9248
	v_exp_f32_e32 v225, v70
	v_pk_add_f32 v[64:65], v[164:165], v[64:65]
	v_exp_f32_e32 v227, v71
	v_pk_add_f32 v[64:65], v[208:209], v[64:65]
	v_cvt_pk_bf16_f32 v66, v211, v223
	s_waitcnt lgkmcnt(4)
	v_mfma_f32_32x32x16_bf16 v[48:63], v[196:199], v[80:83], v[48:63]
	v_pk_add_f32 v[64:65], v[210:211], v[64:65]
	v_cvt_pk_bf16_f32 v67, v225, v227
	v_pk_add_f32 v[64:65], v[222:223], v[64:65]
	v_pk_add_f32 v[64:65], v[224:225], v[64:65]
	s_nop 0
	v_pk_add_f32 v[190:191], v[226:227], v[64:65]
	s_waitcnt lgkmcnt(2)
	v_mfma_f32_32x32x16_bf16 v[32:47], v[200:203], v[80:83], v[32:47]
	v_cvt_pk_bf16_f32 v64, v131, v135
	v_cvt_pk_bf16_f32 v65, v165, v209
	s_waitcnt lgkmcnt(0)
	v_mfma_f32_32x32x16_bf16 v[80:95], v[84:87], v[108:111], 0
	v_mfma_f32_32x32x16_bf16 v[80:95], v[204:207], v[104:107], v[80:95]
	v_exp_f32_e32 v189, v72
	v_exp_f32_e32 v187, v73
	v_exp_f32_e32 v185, v74
	v_exp_f32_e32 v183, v75
	v_exp_f32_e32 v181, v76
	v_exp_f32_e32 v177, v77
	v_exp_f32_e32 v175, v78
	v_exp_f32_e32 v173, v79
	v_cvt_pk_bf16_f32 v68, v189, v187
	v_cvt_pk_bf16_f32 v69, v185, v183
	v_cvt_pk_bf16_f32 v70, v181, v177
	v_cvt_pk_bf16_f32 v71, v175, v173
	s_waitcnt vmcnt(1)
	ds_write_b128 v166, v[120:123]
	s_waitcnt vmcnt(0)
	ds_write_b128 v167, v[124:127]
	global_load_dwordx4 v[128:131], v[128:129], off offset:1536
	s_nop 0
	global_load_dwordx4 v[132:135], v[132:133], off offset:1536
	v_mfma_f32_32x32x16_bf16 v[16:31], v[116:119], v[64:67], v[16:31]
	ds_read_b128 v[72:75], v160 offset:9280
	ds_read_b128 v[112:115], v160 offset:9312
	v_exp_f32_e32 v164, v80
	v_exp_f32_e32 v226, v81
	v_exp_f32_e32 v228, v82
	v_exp_f32_e32 v230, v83
	v_exp_f32_e32 v232, v84
	v_exp_f32_e32 v234, v85
	v_mfma_f32_32x32x16_bf16 v[0:15], v[192:195], v[64:67], v[0:15]
	v_exp_f32_e32 v236, v86
	v_cvt_pk_bf16_f32 v80, v164, v226
	v_cvt_pk_bf16_f32 v81, v228, v230
	v_cvt_pk_bf16_f32 v82, v232, v234
	v_mfma_f32_32x32x16_bf16 v[16:31], v[196:199], v[68:71], v[16:31]
	v_mfma_f32_32x32x16_bf16 v[0:15], v[200:203], v[68:71], v[0:15]
	v_exp_f32_e32 v200, v87
	s_nop 0
	v_cvt_pk_bf16_f32 v83, v236, v200
	s_waitcnt lgkmcnt(0)
	v_mfma_f32_32x32x16_bf16 v[64:79], v[72:75], v[100:103], 0
	v_mfma_f32_32x32x16_bf16 v[64:79], v[112:115], v[96:99], v[64:79]
	ds_read_b64_tr_b16 v[112:113], v147 offset:49152
	ds_read_b64_tr_b16 v[114:115], v147 offset:50688
	ds_read_b64_tr_b16 v[118:119], v147 offset:50752
	ds_read_b64_tr_b16 v[116:117], v147 offset:49216
	ds_read_b64_tr_b16 v[120:121], v147 offset:52224
	ds_read_b64_tr_b16 v[122:123], v147 offset:53760
	ds_read_b64_tr_b16 v[126:127], v147 offset:53824
	ds_read_b64_tr_b16 v[124:125], v147 offset:52288
	v_exp_f32_e32 v208, v88
	v_exp_f32_e32 v206, v89
	v_exp_f32_e32 v204, v90
	v_exp_f32_e32 v202, v91
	v_exp_f32_e32 v198, v92
	v_exp_f32_e32 v196, v93
	v_exp_f32_e32 v194, v94
	v_exp_f32_e32 v192, v95
	v_cvt_pk_bf16_f32 v84, v208, v206
	v_cvt_pk_bf16_f32 v85, v204, v202
	v_cvt_pk_bf16_f32 v86, v198, v196
	v_cvt_pk_bf16_f32 v87, v194, v192
	s_waitcnt lgkmcnt(6)
	v_mfma_f32_32x32x16_bf16 v[48:63], v[112:115], v[80:83], v[48:63]
	v_exp_f32_e32 v165, v64
	v_exp_f32_e32 v227, v65
	v_exp_f32_e32 v229, v66
	v_exp_f32_e32 v231, v67
	v_exp_f32_e32 v233, v68
	ds_read_b128 v[88:91], v160 offset:13824
	ds_read_b128 v[222:225], v160 offset:13856
	s_waitcnt lgkmcnt(6)
	v_mfma_f32_32x32x16_bf16 v[32:47], v[116:119], v[80:83], v[32:47]
	v_exp_f32_e32 v235, v69
	v_pk_add_f32 v[64:65], v[226:227], v[164:165]
	v_exp_f32_e32 v237, v70
	v_pk_add_f32 v[64:65], v[228:229], v[64:65]
	v_exp_f32_e32 v201, v71
	v_pk_add_f32 v[64:65], v[230:231], v[64:65]
	v_cvt_pk_bf16_f32 v66, v233, v235
	s_waitcnt lgkmcnt(4)
	v_mfma_f32_32x32x16_bf16 v[48:63], v[120:123], v[84:87], v[48:63]
	v_pk_add_f32 v[64:65], v[232:233], v[64:65]
	v_cvt_pk_bf16_f32 v67, v237, v201
	v_pk_add_f32 v[64:65], v[234:235], v[64:65]
	v_pk_add_f32 v[210:211], v[236:237], v[64:65]
	v_cvt_pk_bf16_f32 v64, v165, v227
	v_cvt_pk_bf16_f32 v65, v229, v231
	s_waitcnt lgkmcnt(1)
	v_mfma_f32_32x32x16_bf16 v[32:47], v[124:127], v[84:87], v[32:47]
	v_mfma_f32_32x32x16_bf16 v[80:95], v[88:91], v[108:111], 0
	s_waitcnt lgkmcnt(0)
	v_mfma_f32_32x32x16_bf16 v[80:95], v[222:225], v[104:107], v[80:95]
	v_exp_f32_e32 v209, v72
	v_exp_f32_e32 v207, v73
	v_exp_f32_e32 v205, v74
	v_exp_f32_e32 v203, v75
	v_exp_f32_e32 v199, v76
	v_exp_f32_e32 v197, v77
	v_exp_f32_e32 v195, v78
	v_exp_f32_e32 v193, v79
	v_cvt_pk_bf16_f32 v68, v209, v207
	v_cvt_pk_bf16_f32 v69, v205, v203
	v_cvt_pk_bf16_f32 v70, v199, v197
	v_cvt_pk_bf16_f32 v71, v195, v193
	v_mfma_f32_32x32x16_bf16 v[16:31], v[112:115], v[64:67], v[16:31]
	ds_read_b128 v[72:75], v160 offset:13888
	ds_read_b128 v[222:225], v160 offset:13920
	v_exp_f32_e32 v164, v80
	v_exp_f32_e32 v226, v81
	v_exp_f32_e32 v228, v82
	v_exp_f32_e32 v230, v83
	v_exp_f32_e32 v232, v84
	v_exp_f32_e32 v234, v85
	v_mfma_f32_32x32x16_bf16 v[0:15], v[116:119], v[64:67], v[0:15]
	v_exp_f32_e32 v236, v86
	v_exp_f32_e32 v238, v87
	v_cvt_pk_bf16_f32 v80, v164, v226
	v_cvt_pk_bf16_f32 v81, v228, v230
	v_cvt_pk_bf16_f32 v82, v232, v234
	v_cvt_pk_bf16_f32 v83, v236, v238
	v_mfma_f32_32x32x16_bf16 v[16:31], v[120:123], v[68:71], v[16:31]
	v_mfma_f32_32x32x16_bf16 v[0:15], v[124:127], v[68:71], v[0:15]
	s_waitcnt lgkmcnt(0)
; DI void diff_mfma_phase(const Args& A, int wave_s, int l, bool need_ctx, LAS unsigned char* lds) {
;     ...
;             for (int g = 0; g < 8; ++g) {
;                 const int c = g & 1, sub = g >> 1;
;                 bf16x8 kB0, kB1; f32x16 Sn;
;                 if (g < 7) { LAS unsigned char* kp = kl + (32 * ((g + 1) >> 1)) * KV_PITCH + (c ^ 1) * 64; kB0 = *(LAS bf16x8*)(kp); kB1 = *(LAS bf16x8*)(kp + 32); }
;                 if (c == 0) { O[1][0] = MFMA32(Vs[0], Pp0, O[1][0]); O[1][1] = MFMA32(Vs[2], Pp0, O[1][1]); O[1][0] = MFMA32(Vs[1], Pp1, O[1][0]); O[1][1] = MFMA32(Vs[3], Pp1, O[1][1]); }
;                 else        { O[0][0] = MFMA32(Vs[0], Pp0, O[0][0]); O[0][1] = MFMA32(Vs[2], Pp0, O[0][1]); O[0][0] = MFMA32(Vs[1], Pp1, O[0][0]); O[0][1] = MFMA32(Vs[3], Pp1, O[0][1]); }
;                 float t = 0.f;
; #pragma unroll
;                 for (int i = 0; i < 8; ++i) { Sc[i] = __builtin_amdgcn_exp2f(Sc[i]); t += Sc[i]; }
;                 const bf16x8 Pn0 = PACK8(Sc, 0);
;                 __builtin_amdgcn_sched_barrier(0);
;                 if (g < 7) { Sn = MFMA32(kB0, Qf[c ^ 1][0], negM); Sn = MFMA32(kB1, Qf[c ^ 1][1], Sn); }
;                 __builtin_amdgcn_sched_barrier(0);
;                 if (c == 0) { LAS unsigned char* vp = Vb + (32 * sub) * VP + voff; Vs[0] = tr_pairV(vp); Vs[1] = tr_pairV(vp + 16 * VP); Vs[2] = tr_pairV(vp + 64); Vs[3] = tr_pairV(vp + 16 * VP + 64); }
; #pragma unroll
;                 for (int i = 8; i < 16; ++i) { Sc[i] = __builtin_amdgcn_exp2f(Sc[i]); t += Sc[i]; }
;                 if (c == 0) ls0 += t; else ls1 += t;
;                 Pp0 = Pn0; Pp1 = PACK8(Sc, 1);
;                 if (g < 7) Sc = Sn;
;                 __builtin_amdgcn_sched_barrier(0);
;                 if (g == 3 && it + 1 < ntiles) {
;                     LAS unsigned char* kb2 = lds + (cur ^ 1) * DT_IMG;
;                     *(LAS v4u*)(kb2 + srow * KV_PITCH + sch * 16) = kreg[0]; *(LAS v4u*)(kb2 + (srow + 64) * KV_PITCH + sch * 16) = kreg[1];
;                     const int kr0 = (it + 1 < 64 ? kbase0 : kbase1) + (it + 1) * DT_ROWS;
;                     const char* vb_ = (const char*)(C.P + (size_t)kr0 * INW + CC_V + hd * 64);
;                     kreg[0] = *(const v4u*)(vb_ + sgoff); kreg[1] = *(const v4u*)(vb_ + (size_t)64 * INW * 2 + sgoff);
;                     __builtin_amdgcn_sched_barrier(0);
;                 }
;             }
	v_mfma_f32_32x32x16_bf16 v[64:79], v[72:75], v[100:103], 0
	v_mfma_f32_32x32x16_bf16 v[64:79], v[222:225], v[96:99], v[64:79]
	ds_read_b64_tr_b16 v[120:121], v147 offset:55296
	ds_read_b64_tr_b16 v[122:123], v147 offset:56832
	ds_read_b64_tr_b16 v[126:127], v147 offset:56896
	ds_read_b64_tr_b16 v[124:125], v147 offset:55360
	ds_read_b64_tr_b16 v[116:117], v147 offset:58368
	ds_read_b64_tr_b16 v[118:119], v147 offset:59904
	ds_read_b64_tr_b16 v[114:115], v147 offset:59968
	ds_read_b64_tr_b16 v[112:113], v147 offset:58432
	v_exp_f32_e32 v222, v88
	v_exp_f32_e32 v224, v89
	v_exp_f32_e32 v240, v90
	v_exp_f32_e32 v242, v91
	v_exp_f32_e32 v244, v92
	v_exp_f32_e32 v246, v93
	v_exp_f32_e32 v250, v94
	v_exp_f32_e32 v166, v95
	v_cvt_pk_bf16_f32 v84, v222, v224
	v_cvt_pk_bf16_f32 v85, v240, v242
	v_cvt_pk_bf16_f32 v86, v244, v246
	v_cvt_pk_bf16_f32 v87, v250, v166
	s_waitcnt lgkmcnt(6)
	v_mfma_f32_32x32x16_bf16 v[48:63], v[120:123], v[80:83], v[48:63]
	v_exp_f32_e32 v165, v64
	v_exp_f32_e32 v227, v65
	v_exp_f32_e32 v229, v66
	v_exp_f32_e32 v231, v67
	v_exp_f32_e32 v233, v68
	v_exp_f32_e32 v235, v69
	s_waitcnt lgkmcnt(4)
	v_mfma_f32_32x32x16_bf16 v[32:47], v[124:127], v[80:83], v[32:47]
	v_exp_f32_e32 v237, v70
	v_exp_f32_e32 v239, v71
	v_pk_add_f32 v[64:65], v[226:227], v[164:165]
	v_cvt_pk_bf16_f32 v88, v165, v227
	v_pk_add_f32 v[64:65], v[228:229], v[64:65]
	v_cvt_pk_bf16_f32 v89, v229, v231
	v_pk_add_f32 v[64:65], v[230:231], v[64:65]
	s_waitcnt lgkmcnt(2)
	v_mfma_f32_32x32x16_bf16 v[48:63], v[116:119], v[84:87], v[48:63]
	v_pk_add_f32 v[64:65], v[232:233], v[64:65]
	v_cvt_pk_bf16_f32 v90, v233, v235
	v_cvt_pk_bf16_f32 v91, v237, v239
	v_pk_add_f32 v[64:65], v[234:235], v[64:65]
	s_waitcnt lgkmcnt(0)
	v_mfma_f32_32x32x16_bf16 v[32:47], v[112:115], v[84:87], v[32:47]
	v_exp_f32_e32 v223, v72
	v_exp_f32_e32 v225, v73
	v_exp_f32_e32 v241, v74
	v_pk_add_f32 v[66:67], v[170:171], v[178:179]
	v_pk_add_f32 v[68:69], v[188:189], v[190:191]
	v_pk_add_f32 v[70:71], v[200:201], v[210:211]
	v_pk_add_f32 v[64:65], v[236:237], v[64:65]
	v_exp_f32_e32 v243, v75
	v_pk_add_f32 v[66:67], v[168:169], v[66:67]
	v_pk_add_f32 v[68:69], v[186:187], v[68:69]
	v_pk_add_f32 v[70:71], v[208:209], v[70:71]
	v_pk_add_f32 v[64:65], v[238:239], v[64:65]
	v_exp_f32_e32 v245, v76
	v_pk_add_f32 v[66:67], v[158:159], v[66:67]
	v_pk_add_f32 v[68:69], v[184:185], v[68:69]
	v_pk_add_f32 v[70:71], v[206:207], v[70:71]
	v_pk_add_f32 v[64:65], v[222:223], v[64:65]
	v_exp_f32_e32 v247, v77
	v_pk_add_f32 v[66:67], v[156:157], v[66:67]
	v_pk_add_f32 v[68:69], v[182:183], v[68:69]
	v_pk_add_f32 v[70:71], v[204:205], v[70:71]
	v_pk_add_f32 v[64:65], v[224:225], v[64:65]
	v_exp_f32_e32 v251, v78
	v_pk_add_f32 v[66:67], v[154:155], v[66:67]
	v_pk_add_f32 v[68:69], v[180:181], v[68:69]
	v_pk_add_f32 v[70:71], v[202:203], v[70:71]
	v_pk_add_f32 v[64:65], v[240:241], v[64:65]
	v_exp_f32_e32 v167, v79
	v_pk_add_f32 v[66:67], v[152:153], v[66:67]
	v_pk_add_f32 v[68:69], v[176:177], v[68:69]
	v_pk_add_f32 v[70:71], v[198:199], v[70:71]
	v_pk_add_f32 v[64:65], v[242:243], v[64:65]
	v_pk_add_f32 v[66:67], v[150:151], v[66:67]
	v_pk_add_f32 v[68:69], v[174:175], v[68:69]
	v_pk_add_f32 v[70:71], v[196:197], v[70:71]
	v_pk_add_f32 v[64:65], v[244:245], v[64:65]
	v_pk_add_f32 v[66:67], v[148:149], v[66:67]
	v_pk_add_f32 v[68:69], v[172:173], v[68:69]
	v_pk_add_f32 v[70:71], v[194:195], v[70:71]
	v_pk_add_f32 v[64:65], v[246:247], v[64:65]
	v_pk_add_f32 v[66:67], v[66:67], v[68:69]
	v_pk_add_f32 v[68:69], v[192:193], v[70:71]
	v_pk_add_f32 v[64:65], v[250:251], v[64:65]
	v_pk_add_f32 v[66:67], v[66:67], v[68:69]
	v_pk_add_f32 v[64:65], v[166:167], v[64:65]
	v_cvt_pk_bf16_f32 v92, v223, v225
	v_cvt_pk_bf16_f32 v93, v241, v243
	v_cvt_pk_bf16_f32 v94, v245, v247
	v_cvt_pk_bf16_f32 v95, v251, v167
	v_pk_add_f32 v[148:149], v[66:67], v[64:65]
	s_mulk_i32 s15, 0x6000
	s_add_i32 s15, s15, 0
	s_add_u32 s6, s6, 0x80
	s_addc_u32 s7, s7, 0
	v_add3_u32 v64, s15, v217, v212
	v_add3_u32 v65, s15, v216, v212
	s_cmp_eq_u32 s13, s14
	s_mov_b32 s15, s14
	s_waitcnt vmcnt(1)
	ds_write_b128 v65, v[128:131] offset:36864
	s_waitcnt vmcnt(0)
	ds_write_b128 v64, v[132:135] offset:36864
	s_waitcnt lgkmcnt(0)
	s_barrier
	s_cbranch_scc0 .LBB0_406
; DI void diff_mfma_phase(const Args& A, int wave_s, int l, bool need_ctx, LAS unsigned char* lds) {
;     ...
;         for (int it = 0; it < ntiles; ++it) {
;             const int cur = it & 1;
;             if (it + 1 < ntiles) { const int kr0 = (it + 1 < 64 ? kbase0 : kbase1) + (it + 1) * DT_ROWS;
;                 const char* kb_ = (const char*)(C.P + (size_t)kr0 * INW + CC_K + hd * 64);
;                 kreg[0] = *(const v4u*)(kb_ + sgoff); kreg[1] = *(const v4u*)(kb_ + (size_t)64 * INW * 2 + sgoff); }
;             LAS unsigned char* Kb = lds + cur * DT_IMG; LAS unsigned char* Vb = lds + VOFF0 + cur * DV_IMG;
;             LAS unsigned char* kl = Kb + r * KV_PITCH + h * 16;
;             f32x16 Sc;
;             { const bf16x8 kA0 = *(LAS bf16x8*)(kl), kA1 = *(LAS bf16x8*)(kl + 32); Sc = MFMA32(kA0, Qf[0][0], negM); Sc = MFMA32(kA1, Qf[0][1], Sc); }
; #pragma unroll
;             for (int g = 0; g < 8; ++g) {
;                 const int c = g & 1, sub = g >> 1;
;                 bf16x8 kB0, kB1; f32x16 Sn;
;                 if (g < 7) { LAS unsigned char* kp = kl + (32 * ((g + 1) >> 1)) * KV_PITCH + (c ^ 1) * 64; kB0 = *(LAS bf16x8*)(kp); kB1 = *(LAS bf16x8*)(kp + 32); }
;                 if (c == 0) { O[1][0] = MFMA32(Vs[0], Pp0, O[1][0]); O[1][1] = MFMA32(Vs[2], Pp0, O[1][1]); O[1][0] = MFMA32(Vs[1], Pp1, O[1][0]); O[1][1] = MFMA32(Vs[3], Pp1, O[1][1]); }
;                 else        { O[0][0] = MFMA32(Vs[0], Pp0, O[0][0]); O[0][1] = MFMA32(Vs[2], Pp0, O[0][1]); O[0][0] = MFMA32(Vs[1], Pp1, O[0][0]); O[0][1] = MFMA32(Vs[3], Pp1, O[0][1]); }
;                 float t = 0.f;
; #pragma unroll
;                 for (int i = 0; i < 8; ++i) { Sc[i] = __builtin_amdgcn_exp2f(Sc[i]); t += Sc[i]; }
;                 const bf16x8 Pn0 = PACK8(Sc, 0);
;                 __builtin_amdgcn_sched_barrier(0);
;                 if (g < 7) { Sn = MFMA32(kB0, Qf[c ^ 1][0], negM); Sn = MFMA32(kB1, Qf[c ^ 1][1], Sn); }
;                 __builtin_amdgcn_sched_barrier(0);
;                 if (c == 0) { LAS unsigned char* vp = Vb + (32 * sub) * VP + voff; Vs[0] = tr_pairV(vp); Vs[1] = tr_pairV(vp + 16 * VP); Vs[2] = tr_pairV(vp + 64); Vs[3] = tr_pairV(vp + 16 * VP + 64); }
; #pragma unroll
;                 for (int i = 8; i < 16; ++i) { Sc[i] = __builtin_amdgcn_exp2f(Sc[i]); t += Sc[i]; }
;                 if (c == 0) ls0 += t; else ls1 += t;
	s_and_b32 s6, s13, 1
	s_mul_i32 s7, s6, 0x4800
	v_add_u32_e32 v135, s7, v218
	ds_read_b128 v[64:67], v135
	v_mfma_f32_32x32x16_bf16 v[16:31], v[120:123], v[88:91], v[16:31]
	s_mulk_i32 s6, 0x6000
	v_add_u32_e32 v134, s6, v219
	s_waitcnt lgkmcnt(0)
	v_mfma_f32_32x32x16_bf16 v[72:87], v[64:67], v[108:111], 0
	ds_read_b128 v[64:67], v135 offset:32
	v_mfma_f32_32x32x16_bf16 v[0:15], v[124:127], v[88:91], v[0:15]
	s_waitcnt lgkmcnt(0)
	v_mfma_f32_32x32x16_bf16 v[72:87], v[64:67], v[104:107], v[72:87]
	ds_read_b128 v[64:67], v135 offset:64
	ds_read_b128 v[88:91], v135 offset:96
	v_mfma_f32_32x32x16_bf16 v[16:31], v[116:119], v[92:95], v[16:31]
	s_nop 8
	v_exp_f32_e32 v68, v72
	v_exp_f32_e32 v158, v73
	v_exp_f32_e32 v164, v74
	v_exp_f32_e32 v176, v75
	v_exp_f32_e32 v178, v76
	v_exp_f32_e32 v180, v77
	v_exp_f32_e32 v182, v78
	v_exp_f32_e32 v184, v79
	v_add_f32_e32 v160, 0, v68
	v_cvt_pk_bf16_f32 v116, v68, v158
	v_cvt_pk_bf16_f32 v117, v164, v176
	v_cvt_pk_bf16_f32 v118, v178, v180
	v_cvt_pk_bf16_f32 v119, v182, v184
	v_mfma_f32_32x32x16_bf16 v[0:15], v[112:115], v[92:95], v[0:15]
	s_waitcnt lgkmcnt(0)
	v_mfma_f32_32x32x16_bf16 v[64:79], v[64:67], v[100:103], 0
	v_mfma_f32_32x32x16_bf16 v[64:79], v[88:91], v[96:99], v[64:79]
	ds_read_b64_tr_b16 v[150:151], v134 offset:36864
	ds_read_b64_tr_b16 v[152:153], v134 offset:38400
	ds_read_b64_tr_b16 v[156:157], v134 offset:38464
	ds_read_b64_tr_b16 v[154:155], v134 offset:36928
	ds_read_b64_tr_b16 v[168:169], v134 offset:39936
	ds_read_b64_tr_b16 v[170:171], v134 offset:41472
	ds_read_b64_tr_b16 v[174:175], v134 offset:41536
	ds_read_b64_tr_b16 v[172:173], v134 offset:40000
	v_exp_f32_e32 v112, v80
	v_exp_f32_e32 v186, v81
	v_exp_f32_e32 v188, v82
	v_exp_f32_e32 v190, v83
	v_exp_f32_e32 v192, v84
	v_exp_f32_e32 v194, v85
	v_exp_f32_e32 v196, v86
	v_exp_f32_e32 v198, v87
	v_cvt_pk_bf16_f32 v80, v112, v186
	v_cvt_pk_bf16_f32 v81, v188, v190
	v_cvt_pk_bf16_f32 v82, v192, v194
	v_cvt_pk_bf16_f32 v83, v196, v198
	s_waitcnt lgkmcnt(6)
	v_mfma_f32_32x32x16_bf16 v[48:63], v[150:153], v[116:119], v[48:63]
	ds_read_b128 v[84:87], v135 offset:4608
	ds_read_b128 v[120:123], v135 offset:4640
	v_exp_f32_e32 v64, v64
	v_exp_f32_e32 v202, v65
	v_exp_f32_e32 v204, v66
	v_exp_f32_e32 v206, v67
	v_exp_f32_e32 v208, v68
	v_exp_f32_e32 v132, v69
	s_waitcnt lgkmcnt(6)
	v_mfma_f32_32x32x16_bf16 v[32:47], v[154:157], v[116:119], v[32:47]
	v_exp_f32_e32 v130, v70
	v_exp_f32_e32 v114, v71
	v_add_f32_e32 v200, 0, v64
	v_cvt_pk_bf16_f32 v64, v64, v202
	v_cvt_pk_bf16_f32 v65, v204, v206
	v_cvt_pk_bf16_f32 v66, v208, v132
	v_cvt_pk_bf16_f32 v67, v130, v114
	s_waitcnt lgkmcnt(2)
	v_mfma_f32_32x32x16_bf16 v[48:63], v[168:171], v[80:83], v[48:63]
	v_mfma_f32_32x32x16_bf16 v[32:47], v[172:175], v[80:83], v[32:47]
	s_waitcnt lgkmcnt(0)
	v_mfma_f32_32x32x16_bf16 v[80:95], v[84:87], v[108:111], 0
	v_mfma_f32_32x32x16_bf16 v[80:95], v[120:123], v[104:107], v[80:95]
	v_exp_f32_e32 v210, v72
	v_exp_f32_e32 v116, v73
	v_exp_f32_e32 v120, v74
	v_exp_f32_e32 v118, v75
	v_exp_f32_e32 v124, v76
	v_exp_f32_e32 v122, v77
	v_exp_f32_e32 v128, v78
	v_exp_f32_e32 v126, v79
	v_cvt_pk_bf16_f32 v68, v210, v116
	v_cvt_pk_bf16_f32 v69, v120, v118
	v_cvt_pk_bf16_f32 v70, v124, v122
	v_cvt_pk_bf16_f32 v71, v128, v126
	v_mfma_f32_32x32x16_bf16 v[16:31], v[150:153], v[64:67], v[16:31]
	v_exp_f32_e32 v159, v80
	v_exp_f32_e32 v165, v81
	ds_read_b128 v[72:75], v135 offset:4672
	ds_read_b128 v[150:153], v135 offset:4704
	v_exp_f32_e32 v177, v82
	v_exp_f32_e32 v179, v83
	v_exp_f32_e32 v181, v84
	v_exp_f32_e32 v183, v85
	v_mfma_f32_32x32x16_bf16 v[0:15], v[154:157], v[64:67], v[0:15]
	v_exp_f32_e32 v185, v86
	v_exp_f32_e32 v113, v87
	v_pk_add_f32 v[64:65], v[158:159], v[160:161]
	v_cvt_pk_bf16_f32 v80, v159, v165
	v_pk_add_f32 v[64:65], v[164:165], v[64:65]
	v_cvt_pk_bf16_f32 v81, v177, v179
	v_pk_add_f32 v[64:65], v[176:177], v[64:65]
	v_mfma_f32_32x32x16_bf16 v[16:31], v[168:171], v[68:71], v[16:31]
	v_add_f32_e64 v222, v178, v64
	v_add_f32_e64 v223, v179, v65
	v_cvt_pk_bf16_f32 v82, v181, v183
	v_cvt_pk_bf16_f32 v83, v185, v113
	v_mfma_f32_32x32x16_bf16 v[0:15], v[172:175], v[68:71], v[0:15]
	s_waitcnt lgkmcnt(0)
	v_mfma_f32_32x32x16_bf16 v[64:79], v[72:75], v[100:103], 0
	v_mfma_f32_32x32x16_bf16 v[64:79], v[150:153], v[96:99], v[64:79]
	ds_read_b64_tr_b16 v[150:151], v134 offset:43008
	ds_read_b64_tr_b16 v[152:153], v134 offset:44544
	ds_read_b64_tr_b16 v[156:157], v134 offset:44608
	ds_read_b64_tr_b16 v[154:155], v134 offset:43072
	ds_read_b64_tr_b16 v[168:169], v134 offset:46080
	ds_read_b64_tr_b16 v[170:171], v134 offset:47616
	ds_read_b64_tr_b16 v[174:175], v134 offset:47680
	ds_read_b64_tr_b16 v[172:173], v134 offset:46144
	v_exp_f32_e32 v187, v88
	v_pk_add_f32 v[84:85], v[180:181], v[222:223]
	v_exp_f32_e32 v189, v89
	v_pk_add_f32 v[84:85], v[182:183], v[84:85]
	v_exp_f32_e32 v191, v90
	v_pk_add_f32 v[84:85], v[184:185], v[84:85]
	v_exp_f32_e32 v193, v91
	v_pk_add_f32 v[84:85], v[112:113], v[84:85]
	v_exp_f32_e32 v195, v92
	v_pk_add_f32 v[84:85], v[186:187], v[84:85]
	v_exp_f32_e32 v197, v93
	v_pk_add_f32 v[84:85], v[188:189], v[84:85]
	v_exp_f32_e32 v199, v94
	v_pk_add_f32 v[84:85], v[190:191], v[84:85]
	v_exp_f32_e32 v87, v95
	v_pk_add_f32 v[84:85], v[192:193], v[84:85]
	v_mov_b32_e32 v86, v148
	v_pk_add_f32 v[84:85], v[194:195], v[84:85]
	s_nop 0
	v_pk_add_f32 v[84:85], v[196:197], v[84:85]
	s_nop 0
	v_pk_add_f32 v[84:85], v[198:199], v[84:85]
	s_nop 0
	v_pk_add_f32 v[112:113], v[86:87], v[84:85]
	v_cvt_pk_bf16_f32 v84, v187, v189
	v_cvt_pk_bf16_f32 v85, v191, v193
	v_cvt_pk_bf16_f32 v86, v195, v197
	v_cvt_pk_bf16_f32 v87, v199, v87
	s_waitcnt lgkmcnt(6)
; DI void diff_mfma_phase(const Args& A, int wave_s, int l, bool need_ctx, LAS unsigned char* lds) {
;     ...
;         for (int it = 0; it < ntiles; ++it) {
;             const int cur = it & 1;
;             if (it + 1 < ntiles) { const int kr0 = (it + 1 < 64 ? kbase0 : kbase1) + (it + 1) * DT_ROWS;
;                 const char* kb_ = (const char*)(C.P + (size_t)kr0 * INW + CC_K + hd * 64);
;                 kreg[0] = *(const v4u*)(kb_ + sgoff); kreg[1] = *(const v4u*)(kb_ + (size_t)64 * INW * 2 + sgoff); }
;             LAS unsigned char* Kb = lds + cur * DT_IMG; LAS unsigned char* Vb = lds + VOFF0 + cur * DV_IMG;
;             LAS unsigned char* kl = Kb + r * KV_PITCH + h * 16;
;             f32x16 Sc;
;             { const bf16x8 kA0 = *(LAS bf16x8*)(kl), kA1 = *(LAS bf16x8*)(kl + 32); Sc = MFMA32(kA0, Qf[0][0], negM); Sc = MFMA32(kA1, Qf[0][1], Sc); }
; #pragma unroll
;             for (int g = 0; g < 8; ++g) {
;                 const int c = g & 1, sub = g >> 1;
;                 bf16x8 kB0, kB1; f32x16 Sn;
;                 if (g < 7) { LAS unsigned char* kp = kl + (32 * ((g + 1) >> 1)) * KV_PITCH + (c ^ 1) * 64; kB0 = *(LAS bf16x8*)(kp); kB1 = *(LAS bf16x8*)(kp + 32); }
;                 if (c == 0) { O[1][0] = MFMA32(Vs[0], Pp0, O[1][0]); O[1][1] = MFMA32(Vs[2], Pp0, O[1][1]); O[1][0] = MFMA32(Vs[1], Pp1, O[1][0]); O[1][1] = MFMA32(Vs[3], Pp1, O[1][1]); }
;                 else        { O[0][0] = MFMA32(Vs[0], Pp0, O[0][0]); O[0][1] = MFMA32(Vs[2], Pp0, O[0][1]); O[0][0] = MFMA32(Vs[1], Pp1, O[0][0]); O[0][1] = MFMA32(Vs[3], Pp1, O[0][1]); }
;                 float t = 0.f;
; #pragma unroll
;                 for (int i = 0; i < 8; ++i) { Sc[i] = __builtin_amdgcn_exp2f(Sc[i]); t += Sc[i]; }
;                 const bf16x8 Pn0 = PACK8(Sc, 0);
;                 __builtin_amdgcn_sched_barrier(0);
;                 if (g < 7) { Sn = MFMA32(kB0, Qf[c ^ 1][0], negM); Sn = MFMA32(kB1, Qf[c ^ 1][1], Sn); }
;                 __builtin_amdgcn_sched_barrier(0);
;                 if (c == 0) { LAS unsigned char* vp = Vb + (32 * sub) * VP + voff; Vs[0] = tr_pairV(vp); Vs[1] = tr_pairV(vp + 16 * VP); Vs[2] = tr_pairV(vp + 64); Vs[3] = tr_pairV(vp + 16 * VP + 64); }
; #pragma unroll
;                 for (int i = 8; i < 16; ++i) { Sc[i] = __builtin_amdgcn_exp2f(Sc[i]); t += Sc[i]; }
;                 if (c == 0) ls0 += t; else ls1 += t;
	v_mfma_f32_32x32x16_bf16 v[48:63], v[150:153], v[80:83], v[48:63]
	v_exp_f32_e32 v203, v64
	v_exp_f32_e32 v205, v65
	ds_read_b128 v[88:91], v135 offset:9216
	ds_read_b128 v[176:179], v135 offset:9248
	v_exp_f32_e32 v207, v66
	v_exp_f32_e32 v209, v67
	v_mov_b32_e32 v201, v161
	v_exp_f32_e32 v133, v68
	s_waitcnt lgkmcnt(6)
	v_mfma_f32_32x32x16_bf16 v[32:47], v[154:157], v[80:83], v[32:47]
	v_exp_f32_e32 v131, v69
	v_exp_f32_e32 v115, v70
	v_exp_f32_e32 v211, v71
	v_pk_add_f32 v[64:65], v[202:203], v[200:201]
	v_cvt_pk_bf16_f32 v66, v133, v131
	v_pk_add_f32 v[64:65], v[204:205], v[64:65]
	v_cvt_pk_bf16_f32 v67, v115, v211
	v_pk_add_f32 v[64:65], v[206:207], v[64:65]
	s_waitcnt lgkmcnt(4)
	v_mfma_f32_32x32x16_bf16 v[48:63], v[168:171], v[84:87], v[48:63]
	v_add_f32_e64 v158, v208, v64
	v_add_f32_e64 v159, v209, v65
	v_cvt_pk_bf16_f32 v64, v203, v205
	v_cvt_pk_bf16_f32 v65, v207, v209
	s_waitcnt lgkmcnt(1)
	v_mfma_f32_32x32x16_bf16 v[32:47], v[172:175], v[84:87], v[32:47]
	v_mfma_f32_32x32x16_bf16 v[80:95], v[88:91], v[108:111], 0
	s_waitcnt lgkmcnt(0)
	v_mfma_f32_32x32x16_bf16 v[80:95], v[176:179], v[104:107], v[80:95]
	v_exp_f32_e32 v117, v72
	v_pk_add_f32 v[68:69], v[132:133], v[158:159]
	v_exp_f32_e32 v121, v73
	v_pk_add_f32 v[68:69], v[130:131], v[68:69]
	v_exp_f32_e32 v119, v74
	v_pk_add_f32 v[68:69], v[114:115], v[68:69]
	v_exp_f32_e32 v125, v75
	v_pk_add_f32 v[68:69], v[210:211], v[68:69]
	v_exp_f32_e32 v123, v76
	v_pk_add_f32 v[68:69], v[116:117], v[68:69]
	v_exp_f32_e32 v129, v77
	v_pk_add_f32 v[68:69], v[120:121], v[68:69]
	v_exp_f32_e32 v127, v78
	v_pk_add_f32 v[68:69], v[118:119], v[68:69]
	v_exp_f32_e32 v71, v79
	v_pk_add_f32 v[68:69], v[124:125], v[68:69]
	v_mov_b32_e32 v70, v149
	v_pk_add_f32 v[68:69], v[122:123], v[68:69]
	s_nop 0
	v_pk_add_f32 v[68:69], v[128:129], v[68:69]
	s_nop 0
	v_pk_add_f32 v[68:69], v[126:127], v[68:69]
	s_nop 0
	v_pk_add_f32 v[114:115], v[70:71], v[68:69]
	v_cvt_pk_bf16_f32 v68, v117, v121
	v_cvt_pk_bf16_f32 v69, v119, v125
	v_cvt_pk_bf16_f32 v70, v123, v129
	v_cvt_pk_bf16_f32 v71, v127, v71
	v_mfma_f32_32x32x16_bf16 v[16:31], v[150:153], v[64:67], v[16:31]
	ds_read_b128 v[72:75], v135 offset:9280
	ds_read_b128 v[116:119], v135 offset:9312
	v_exp_f32_e32 v152, v81
	v_exp_f32_e32 v158, v84
	v_exp_f32_e32 v164, v85
	v_mfma_f32_32x32x16_bf16 v[0:15], v[154:157], v[64:67], v[0:15]
	v_exp_f32_e32 v64, v80
	v_exp_f32_e32 v154, v82
	v_exp_f32_e32 v156, v83
	v_cvt_pk_bf16_f32 v82, v158, v164
	v_add_f32_e32 v160, 0, v64
	v_cvt_pk_bf16_f32 v80, v64, v152
	v_cvt_pk_bf16_f32 v81, v154, v156
	v_mfma_f32_32x32x16_bf16 v[16:31], v[168:171], v[68:71], v[16:31]
	v_exp_f32_e32 v168, v86
	v_exp_f32_e32 v170, v87
	s_nop 0
	v_cvt_pk_bf16_f32 v83, v168, v170
	v_mfma_f32_32x32x16_bf16 v[0:15], v[172:175], v[68:71], v[0:15]
	s_waitcnt lgkmcnt(0)
	v_mfma_f32_32x32x16_bf16 v[64:79], v[72:75], v[100:103], 0
	v_mfma_f32_32x32x16_bf16 v[64:79], v[116:119], v[96:99], v[64:79]
	ds_read_b64_tr_b16 v[122:123], v134 offset:49152
	ds_read_b64_tr_b16 v[124:125], v134 offset:50688
	ds_read_b64_tr_b16 v[128:129], v134 offset:50752
	ds_read_b64_tr_b16 v[126:127], v134 offset:49216
	ds_read_b64_tr_b16 v[130:131], v134 offset:52224
	ds_read_b64_tr_b16 v[132:133], v134 offset:53760
	ds_read_b64_tr_b16 v[150:151], v134 offset:53824
	ds_read_b64_tr_b16 v[148:149], v134 offset:52288
	v_exp_f32_e32 v172, v88
	v_exp_f32_e32 v174, v89
	v_exp_f32_e32 v176, v90
	v_exp_f32_e32 v178, v91
	v_exp_f32_e32 v180, v92
	v_exp_f32_e32 v182, v93
	v_exp_f32_e32 v184, v94
	v_exp_f32_e32 v186, v95
	v_cvt_pk_bf16_f32 v84, v172, v174
	v_cvt_pk_bf16_f32 v85, v176, v178
	v_cvt_pk_bf16_f32 v86, v180, v182
	v_cvt_pk_bf16_f32 v87, v184, v186
	s_waitcnt lgkmcnt(6)
	v_mfma_f32_32x32x16_bf16 v[48:63], v[122:125], v[80:83], v[48:63]
	ds_read_b128 v[88:91], v135 offset:13824
	ds_read_b128 v[116:119], v135 offset:13856
	v_exp_f32_e32 v64, v64
	v_exp_f32_e32 v190, v65
	v_exp_f32_e32 v192, v66
	v_exp_f32_e32 v194, v67
	v_exp_f32_e32 v196, v68
	v_exp_f32_e32 v198, v69
	s_waitcnt lgkmcnt(6)
	v_mfma_f32_32x32x16_bf16 v[32:47], v[126:129], v[80:83], v[32:47]
	v_exp_f32_e32 v200, v70
	v_exp_f32_e32 v202, v71
	v_add_f32_e32 v188, 0, v64
	v_cvt_pk_bf16_f32 v64, v64, v190
	v_cvt_pk_bf16_f32 v65, v192, v194
	v_cvt_pk_bf16_f32 v66, v196, v198
	v_cvt_pk_bf16_f32 v67, v200, v202
	s_waitcnt lgkmcnt(2)
	v_mfma_f32_32x32x16_bf16 v[48:63], v[130:133], v[84:87], v[48:63]
	v_mfma_f32_32x32x16_bf16 v[32:47], v[148:151], v[84:87], v[32:47]
	s_waitcnt lgkmcnt(0)
	v_mfma_f32_32x32x16_bf16 v[80:95], v[88:91], v[108:111], 0
	v_mfma_f32_32x32x16_bf16 v[80:95], v[116:119], v[104:107], v[80:95]
	v_exp_f32_e32 v204, v72
	v_exp_f32_e32 v104, v73
	v_exp_f32_e32 v108, v74
	v_exp_f32_e32 v106, v75
	v_exp_f32_e32 v116, v76
	v_exp_f32_e32 v110, v77
	v_exp_f32_e32 v120, v78
	v_exp_f32_e32 v118, v79
	v_cvt_pk_bf16_f32 v68, v204, v104
	v_cvt_pk_bf16_f32 v69, v108, v106
	v_cvt_pk_bf16_f32 v70, v116, v110
	v_cvt_pk_bf16_f32 v71, v120, v118
	v_mfma_f32_32x32x16_bf16 v[16:31], v[122:125], v[64:67], v[16:31]
	v_exp_f32_e32 v153, v80
	v_exp_f32_e32 v155, v81
	ds_read_b128 v[72:75], v135 offset:13888
	ds_read_b128 v[122:125], v135 offset:13920
	v_exp_f32_e32 v157, v82
	v_exp_f32_e32 v159, v83
	v_exp_f32_e32 v165, v84
	v_exp_f32_e32 v169, v85
	v_mfma_f32_32x32x16_bf16 v[0:15], v[126:129], v[64:67], v[0:15]
	v_exp_f32_e32 v171, v86
	v_exp_f32_e32 v173, v87
	v_pk_add_f32 v[64:65], v[152:153], v[160:161]
	v_cvt_pk_bf16_f32 v80, v153, v155
	v_pk_add_f32 v[64:65], v[154:155], v[64:65]
	v_cvt_pk_bf16_f32 v81, v157, v159
	v_pk_add_f32 v[64:65], v[156:157], v[64:65]
	v_mfma_f32_32x32x16_bf16 v[16:31], v[130:133], v[68:71], v[16:31]
	v_add_f32_e64 v126, v158, v64
	v_add_f32_e64 v127, v159, v65
	v_cvt_pk_bf16_f32 v82, v165, v169
	v_cvt_pk_bf16_f32 v83, v171, v173
	v_mfma_f32_32x32x16_bf16 v[0:15], v[148:151], v[68:71], v[0:15]
	s_waitcnt lgkmcnt(0)
; #define LAS __attribute__((address_space(3)))
; DI void diff_mfma_phase(const Args& A, int wave_s, int l, bool need_ctx, LAS unsigned char* lds) {
;     ...
;             for (int g = 0; g < 8; ++g) {
;                 const int c = g & 1, sub = g >> 1;
;                 bf16x8 kB0, kB1; f32x16 Sn;
;                 if (g < 7) { LAS unsigned char* kp = kl + (32 * ((g + 1) >> 1)) * KV_PITCH + (c ^ 1) * 64; kB0 = *(LAS bf16x8*)(kp); kB1 = *(LAS bf16x8*)(kp + 32); }
;                 if (c == 0) { O[1][0] = MFMA32(Vs[0], Pp0, O[1][0]); O[1][1] = MFMA32(Vs[2], Pp0, O[1][1]); O[1][0] = MFMA32(Vs[1], Pp1, O[1][0]); O[1][1] = MFMA32(Vs[3], Pp1, O[1][1]); }
;                 else        { O[0][0] = MFMA32(Vs[0], Pp0, O[0][0]); O[0][1] = MFMA32(Vs[2], Pp0, O[0][1]); O[0][0] = MFMA32(Vs[1], Pp1, O[0][0]); O[0][1] = MFMA32(Vs[3], Pp1, O[0][1]); }
;                 float t = 0.f;
; #pragma unroll
;                 for (int i = 0; i < 8; ++i) { Sc[i] = __builtin_amdgcn_exp2f(Sc[i]); t += Sc[i]; }
;                 const bf16x8 Pn0 = PACK8(Sc, 0);
;                 __builtin_amdgcn_sched_barrier(0);
;                 if (g < 7) { Sn = MFMA32(kB0, Qf[c ^ 1][0], negM); Sn = MFMA32(kB1, Qf[c ^ 1][1], Sn); }
;                 __builtin_amdgcn_sched_barrier(0);
;                 if (c == 0) { LAS unsigned char* vp = Vb + (32 * sub) * VP + voff; Vs[0] = tr_pairV(vp); Vs[1] = tr_pairV(vp + 16 * VP); Vs[2] = tr_pairV(vp + 64); Vs[3] = tr_pairV(vp + 16 * VP + 64); }
; #pragma unroll
;                 for (int i = 8; i < 16; ++i) { Sc[i] = __builtin_amdgcn_exp2f(Sc[i]); t += Sc[i]; }
;                 if (c == 0) ls0 += t; else ls1 += t;
;                 Pp0 = Pn0; Pp1 = PACK8(Sc, 1);
;                 if (g < 7) Sc = Sn;
;     ...
;             if (it + 1 < ntiles) { LAS unsigned char* vb2 = lds + VOFF0 + (cur ^ 1) * DV_IMG;
;                 *(LAS v4u*)(vb2 + srow * VP + sch * 16) = kreg[0]; *(LAS v4u*)(vb2 + (srow + 64) * VP + sch * 16) = kreg[1]; }
;             __syncthreads();
;         }
;         O[1][0] = MFMA32(Vs[0], Pp0, O[1][0]); O[1][1] = MFMA32(Vs[2], Pp0, O[1][1]); O[1][0] = MFMA32(Vs[1], Pp1, O[1][0]); O[1][1] = MFMA32(Vs[3], Pp1, O[1][1]);
;         ls0 += shx_(C.lane, ls0, 32); ls1 += shx_(C.lane, ls1, 32);
;         const float inv0 = 1.f / ls0, inv1 = lam / ls1;
;         float ss = 0.f;
; #pragma unroll
;         for (int mt = 0; mt < 2; ++mt)
; #pragma unroll
	v_mfma_f32_32x32x16_bf16 v[64:79], v[72:75], v[100:103], 0
	v_mfma_f32_32x32x16_bf16 v[64:79], v[122:125], v[96:99], v[64:79]
	v_exp_f32_e32 v175, v88
	v_exp_f32_e32 v177, v89
	v_pk_add_f32 v[88:89], v[164:165], v[126:127]
	ds_read_b64_tr_b16 v[84:85], v134 offset:55296
	ds_read_b64_tr_b16 v[86:87], v134 offset:56832
	ds_read_b64_tr_b16 v[98:99], v134 offset:56896
	ds_read_b64_tr_b16 v[96:97], v134 offset:55360
	ds_read_b64_tr_b16 v[100:101], v134 offset:58368
	ds_read_b64_tr_b16 v[102:103], v134 offset:59904
	ds_read_b64_tr_b16 v[124:125], v134 offset:59968
	ds_read_b64_tr_b16 v[122:123], v134 offset:58432
	v_pk_add_f32 v[88:89], v[168:169], v[88:89]
	v_exp_f32_e32 v179, v90
	v_pk_add_f32 v[88:89], v[170:171], v[88:89]
	v_exp_f32_e32 v181, v91
	v_pk_add_f32 v[88:89], v[172:173], v[88:89]
	v_exp_f32_e32 v183, v92
	v_pk_add_f32 v[88:89], v[174:175], v[88:89]
	v_exp_f32_e32 v185, v93
	v_pk_add_f32 v[88:89], v[176:177], v[88:89]
	v_exp_f32_e32 v187, v94
	v_exp_f32_e32 v92, v95
	v_pk_add_f32 v[88:89], v[178:179], v[88:89]
	v_pk_add_f32 v[90:91], v[112:113], v[112:113] op_sel:[0,1] op_sel_hi:[1,0]
	v_pk_add_f32 v[88:89], v[180:181], v[88:89]
	v_mov_b32_e32 v91, v92
	v_pk_add_f32 v[88:89], v[182:183], v[88:89]
	s_nop 0
	v_pk_add_f32 v[88:89], v[184:185], v[88:89]
	s_nop 0
	v_pk_add_f32 v[88:89], v[186:187], v[88:89]
	s_nop 0
	v_pk_add_f32 v[88:89], v[90:91], v[88:89]
	v_cvt_pk_bf16_f32 v90, v183, v185
	v_add_f32_e32 v93, v88, v89
	v_cvt_pk_bf16_f32 v88, v175, v177
	v_cvt_pk_bf16_f32 v89, v179, v181
	v_cvt_pk_bf16_f32 v91, v187, v92
	s_waitcnt lgkmcnt(6)
	v_mfma_f32_32x32x16_bf16 v[48:63], v[84:87], v[80:83], v[48:63]
	v_exp_f32_e32 v191, v64
	v_exp_f32_e32 v193, v65
	v_exp_f32_e32 v195, v66
	v_exp_f32_e32 v197, v67
	v_mov_b32_e32 v189, v161
	v_exp_f32_e32 v199, v68
	v_exp_f32_e32 v201, v69
	s_waitcnt lgkmcnt(4)
	v_mfma_f32_32x32x16_bf16 v[32:47], v[96:99], v[80:83], v[32:47]
	v_exp_f32_e32 v203, v70
	v_exp_f32_e32 v205, v71
	v_pk_add_f32 v[64:65], v[190:191], v[188:189]
	v_cvt_pk_bf16_f32 v66, v199, v201
	v_pk_add_f32 v[64:65], v[192:193], v[64:65]
	v_cvt_pk_bf16_f32 v67, v203, v205
	v_pk_add_f32 v[64:65], v[194:195], v[64:65]
	s_waitcnt lgkmcnt(2)
	v_mfma_f32_32x32x16_bf16 v[48:63], v[100:103], v[88:91], v[48:63]
	v_add_f32_e64 v80, v196, v64
	v_add_f32_e64 v81, v197, v65
	v_cvt_pk_bf16_f32 v64, v191, v193
	v_cvt_pk_bf16_f32 v65, v195, v197
	s_waitcnt lgkmcnt(0)
	v_mfma_f32_32x32x16_bf16 v[32:47], v[122:125], v[88:91], v[32:47]
	v_exp_f32_e32 v105, v72
	v_pk_add_f32 v[68:69], v[198:199], v[80:81]
	v_exp_f32_e32 v109, v73
	v_pk_add_f32 v[68:69], v[200:201], v[68:69]
	v_exp_f32_e32 v107, v74
	v_pk_add_f32 v[68:69], v[202:203], v[68:69]
	v_exp_f32_e32 v117, v75
	v_pk_add_f32 v[68:69], v[204:205], v[68:69]
	v_exp_f32_e32 v111, v76
	v_pk_add_f32 v[68:69], v[104:105], v[68:69]
	v_exp_f32_e32 v121, v77
	v_pk_add_f32 v[68:69], v[108:109], v[68:69]
	v_exp_f32_e32 v119, v78
	v_exp_f32_e32 v72, v79
	v_pk_add_f32 v[68:69], v[106:107], v[68:69]
	v_pk_add_f32 v[70:71], v[114:115], v[114:115] op_sel:[0,1] op_sel_hi:[1,0]
	v_pk_add_f32 v[68:69], v[116:117], v[68:69]
	v_mov_b32_e32 v71, v72
	v_pk_add_f32 v[68:69], v[110:111], v[68:69]
	s_nop 0
	v_pk_add_f32 v[68:69], v[120:121], v[68:69]
	s_nop 0
	v_pk_add_f32 v[68:69], v[118:119], v[68:69]
	s_nop 0
	v_pk_add_f32 v[68:69], v[70:71], v[68:69]
	v_cvt_pk_bf16_f32 v70, v111, v121
	v_add_f32_e32 v73, v68, v69
	v_cvt_pk_bf16_f32 v68, v105, v109
	v_cvt_pk_bf16_f32 v69, v107, v117
	v_cvt_pk_bf16_f32 v71, v119, v72
	v_mfma_f32_32x32x16_bf16 v[16:31], v[84:87], v[64:67], v[16:31]
	s_barrier
	s_lshl_b64 s[4:5], s[4:5], 11
	s_add_u32 s4, s88, s4
	s_addc_u32 s5, s89, s5
	s_add_u32 s4, s4, s9
	v_mfma_f32_32x32x16_bf16 v[0:15], v[96:99], v[64:67], v[0:15]
	ds_bpermute_b32 v64, v220, v93
	ds_bpermute_b32 v65, v220, v73
	s_addc_u32 s5, s5, 0
	v_mov_b32_e32 v147, v161
	s_add_i32 s8, s8, s90
	s_waitcnt lgkmcnt(1)
	v_add_f32_e32 v64, v93, v64
	v_div_scale_f32 v66, s[6:7], v64, v64, 1.0
	v_rcp_f32_e32 v67, v66
	v_mfma_f32_32x32x16_bf16 v[16:31], v[100:103], v[68:71], v[16:31]
	s_waitcnt lgkmcnt(0)
	v_add_f32_e32 v65, v73, v65
	v_lshl_add_u64 v[72:73], s[4:5], 0, v[146:147]
	v_lshl_add_u64 v[72:73], v[136:137], 1, v[72:73]
	s_mov_b64 s[4:5], 0x7a00600
	s_cmp_ge_i32 s8, s2
	v_mfma_f32_32x32x16_bf16 v[0:15], v[122:125], v[68:71], v[0:15]
	v_fma_f32 v68, -v66, v67, 1.0
	v_fmac_f32_e32 v67, v68, v67
	v_div_scale_f32 v68, vcc, 1.0, v64, 1.0
	v_mul_f32_e32 v69, v68, v67
	v_fma_f32 v70, -v66, v69, v68
	v_fmac_f32_e32 v69, v70, v67
	v_fma_f32 v66, -v66, v69, v68
	v_div_fmas_f32 v66, v66, v67, v69
	v_div_fixup_f32 v64, v66, v64, 1.0
	v_div_scale_f32 v66, s[6:7], v65, v65, v163
	v_rcp_f32_e32 v67, v66
	s_nop 0
	v_fma_f32 v68, -v66, v67, 1.0
	v_fmac_f32_e32 v67, v68, v67
	v_div_scale_f32 v68, vcc, v163, v65, v163
	v_mul_f32_e32 v69, v68, v67
	v_fma_f32 v70, -v66, v69, v68
	v_fmac_f32_e32 v69, v70, v67
	v_fma_f32 v66, -v66, v69, v68
	v_div_fmas_f32 v66, v66, v67, v69
	v_div_fixup_f32 v66, v66, v65, v163
	v_pk_mul_f32 v[12:13], v[12:13], v[66:67] op_sel_hi:[1,0]
	v_pk_mul_f32 v[14:15], v[14:15], v[66:67] op_sel_hi:[1,0]
	v_pk_fma_f32 v[12:13], v[44:45], v[64:65], v[12:13] op_sel_hi:[1,0,1] neg_lo:[0,0,1] neg_hi:[0,0,1]
	v_pk_fma_f32 v[14:15], v[46:47], v[64:65], v[14:15] op_sel_hi:[1,0,1] neg_lo:[0,0,1] neg_hi:[0,0,1]
	global_load_dwordx4 v[44:47], v[144:145], off
	global_load_dwordx4 v[164:167], v[144:145], off offset:32
	global_load_dwordx4 v[168:171], v[144:145], off offset:64
	global_load_dwordx4 v[172:175], v[144:145], off offset:96
	global_load_dwordx4 v[176:179], v[144:145], off offset:128
	global_load_dwordx4 v[180:183], v[144:145], off offset:160
; DI float shx_(int lane, float v, int m) { return __builtin_bit_cast(float, __builtin_amdgcn_ds_bpermute((lane ^ m) << 2, __builtin_bit_cast(int, v))); }
; DI void diff_mfma_phase(const Args& A, int wave_s, int l, bool need_ctx, LAS unsigned char* lds) {
;     ...
;         const float inv0 = 1.f / ls0, inv1 = lam / ls1;
;         float ss = 0.f;
; #pragma unroll
;         for (int mt = 0; mt < 2; ++mt)
; #pragma unroll
;             for (int i = 0; i < 16; ++i) { const float o = O[0][mt][i] * inv0 - O[1][mt][i] * inv1; O[0][mt][i] = o; ss += o * o; }
;         ss += shx_(C.lane, ss, 32);
;         const float rs = rsqrtf(ss * (1.f / 64.f) + EPS) * (1.f - lam_init);
;         bf16* op = C.MIX + (size_t)qrow0 * 1024 + 768 + hd * 64 + (unsigned)((wave * 32 + r) * 1024);
; #pragma unroll
;         for (int mt = 0; mt < 2; ++mt)
; #pragma unroll
;             for (int g = 0; g < 4; ++g) { const int dv0 = 32 * mt + 8 * g + 4 * h; const f32x4 og = *(const f32x4*)(C.dog + l * 64 + dv0);
	global_load_dwordx4 v[184:187], v[144:145], off offset:192
	global_load_dwordx4 v[188:191], v[144:145], off offset:224
	v_pk_mul_f32 v[0:1], v[0:1], v[66:67] op_sel_hi:[1,0]
	v_pk_mul_f32 v[16:17], v[16:17], v[66:67] op_sel_hi:[1,0]
	v_pk_fma_f32 v[32:33], v[32:33], v[64:65], v[0:1] op_sel_hi:[1,0,1] neg_lo:[0,0,1] neg_hi:[0,0,1]
	v_pk_mul_f32 v[0:1], v[6:7], v[66:67] op_sel_hi:[1,0]
	v_pk_mul_f32 v[18:19], v[18:19], v[66:67] op_sel_hi:[1,0]
	v_pk_fma_f32 v[48:49], v[48:49], v[64:65], v[16:17] op_sel_hi:[1,0,1] neg_lo:[0,0,1] neg_hi:[0,0,1]
	v_pk_fma_f32 v[6:7], v[38:39], v[64:65], v[0:1] op_sel_hi:[1,0,1] neg_lo:[0,0,1] neg_hi:[0,0,1]
	v_pk_mul_f32 v[0:1], v[4:5], v[66:67] op_sel_hi:[1,0]
	v_pk_fma_f32 v[18:19], v[50:51], v[64:65], v[18:19] op_sel_hi:[1,0,1] neg_lo:[0,0,1] neg_hi:[0,0,1]
	v_pk_mul_f32 v[74:75], v[48:49], v[48:49]
	v_pk_fma_f32 v[36:37], v[36:37], v[64:65], v[0:1] op_sel_hi:[1,0,1] neg_lo:[0,0,1] neg_hi:[0,0,1]
	v_pk_mul_f32 v[0:1], v[10:11], v[66:67] op_sel_hi:[1,0]
	v_pk_mul_f32 v[50:51], v[18:19], v[18:19]
	v_pk_mul_f32 v[20:21], v[20:21], v[66:67] op_sel_hi:[1,0]
	v_pk_fma_f32 v[0:1], v[42:43], v[64:65], v[0:1] op_sel_hi:[1,0,1] neg_lo:[0,0,1] neg_hi:[0,0,1]
	v_add_f32_e32 v42, v74, v75
	v_pk_fma_f32 v[20:21], v[52:53], v[64:65], v[20:21] op_sel_hi:[1,0,1] neg_lo:[0,0,1] neg_hi:[0,0,1]
	v_add_f32_e32 v42, v50, v42
	v_pk_mul_f32 v[22:23], v[22:23], v[66:67] op_sel_hi:[1,0]
	v_pk_mul_f32 v[52:53], v[20:21], v[20:21]
	v_add_f32_e32 v42, v51, v42
	v_pk_fma_f32 v[22:23], v[54:55], v[64:65], v[22:23] op_sel_hi:[1,0,1] neg_lo:[0,0,1] neg_hi:[0,0,1]
	v_add_f32_e32 v42, v52, v42
	v_pk_mul_f32 v[54:55], v[22:23], v[22:23]
	v_pk_mul_f32 v[24:25], v[24:25], v[66:67] op_sel_hi:[1,0]
	v_add_f32_e32 v42, v53, v42
	v_pk_fma_f32 v[24:25], v[56:57], v[64:65], v[24:25] op_sel_hi:[1,0,1] neg_lo:[0,0,1] neg_hi:[0,0,1]
	v_add_f32_e32 v42, v54, v42
	v_pk_mul_f32 v[26:27], v[26:27], v[66:67] op_sel_hi:[1,0]
	v_pk_mul_f32 v[56:57], v[24:25], v[24:25]
	v_add_f32_e32 v42, v55, v42
	v_pk_fma_f32 v[26:27], v[58:59], v[64:65], v[26:27] op_sel_hi:[1,0,1] neg_lo:[0,0,1] neg_hi:[0,0,1]
	v_add_f32_e32 v42, v56, v42
	v_pk_mul_f32 v[58:59], v[26:27], v[26:27]
	v_pk_mul_f32 v[28:29], v[28:29], v[66:67] op_sel_hi:[1,0]
	v_add_f32_e32 v42, v57, v42
	v_pk_fma_f32 v[28:29], v[60:61], v[64:65], v[28:29] op_sel_hi:[1,0,1] neg_lo:[0,0,1] neg_hi:[0,0,1]
	v_add_f32_e32 v42, v58, v42
	v_pk_mul_f32 v[30:31], v[30:31], v[66:67] op_sel_hi:[1,0]
	v_pk_mul_f32 v[60:61], v[28:29], v[28:29]
	v_add_f32_e32 v42, v59, v42
	v_pk_fma_f32 v[30:31], v[62:63], v[64:65], v[30:31] op_sel_hi:[1,0,1] neg_lo:[0,0,1] neg_hi:[0,0,1]
	v_add_f32_e32 v42, v60, v42
	v_pk_mul_f32 v[62:63], v[30:31], v[30:31]
	v_add_f32_e32 v42, v61, v42
	v_add_f32_e32 v42, v62, v42
	v_pk_mul_f32 v[2:3], v[2:3], v[66:67] op_sel_hi:[1,0]
	v_pk_mul_f32 v[76:77], v[32:33], v[32:33]
	v_add_f32_e32 v42, v63, v42
	v_pk_fma_f32 v[34:35], v[34:35], v[64:65], v[2:3] op_sel_hi:[1,0,1] neg_lo:[0,0,1] neg_hi:[0,0,1]
	v_add_f32_e32 v42, v76, v42
	v_pk_mul_f32 v[2:3], v[34:35], v[34:35]
	v_add_f32_e32 v42, v77, v42
	v_add_f32_e32 v2, v2, v42
	v_pk_mul_f32 v[4:5], v[36:37], v[36:37]
	v_add_f32_e32 v2, v3, v2
	v_add_f32_e32 v2, v4, v2
	v_pk_mul_f32 v[38:39], v[6:7], v[6:7]
	v_pk_mul_f32 v[8:9], v[8:9], v[66:67] op_sel_hi:[1,0]
	v_add_f32_e32 v2, v5, v2
	v_pk_fma_f32 v[8:9], v[40:41], v[64:65], v[8:9] op_sel_hi:[1,0,1] neg_lo:[0,0,1] neg_hi:[0,0,1]
	v_add_f32_e32 v2, v38, v2
	v_pk_mul_f32 v[40:41], v[8:9], v[8:9]
	v_add_f32_e32 v2, v39, v2
	v_add_f32_e32 v2, v40, v2
	v_pk_mul_f32 v[10:11], v[0:1], v[0:1]
	v_add_f32_e32 v2, v41, v2
	v_add_f32_e32 v2, v10, v2
	v_pk_mul_f32 v[68:69], v[12:13], v[12:13]
	v_add_f32_e32 v2, v11, v2
	v_add_f32_e32 v2, v68, v2
	v_pk_mul_f32 v[70:71], v[14:15], v[14:15]
	v_add_f32_e32 v2, v69, v2
	v_add_f32_e32 v2, v70, v2
	v_add_f32_e32 v2, v71, v2
	ds_bpermute_b32 v3, v220, v2
	v_lshl_add_u64 v[16:17], v[72:73], 0, s[4:5]
	s_mov_b32 s4, 0x7a00000
	s_waitcnt lgkmcnt(0)
; DI unsigned pkbf(float a, float b) { fv2 v = {a, b}; return __builtin_bit_cast(unsigned, __builtin_convertvector(v, bfv2)); }
; DI void diff_mfma_phase(const Args& A, int wave_s, int l, bool need_ctx, LAS unsigned char* lds) {
;     ...
;         const float rs = rsqrtf(ss * (1.f / 64.f) + EPS) * (1.f - lam_init);
;         bf16* op = C.MIX + (size_t)qrow0 * 1024 + 768 + hd * 64 + (unsigned)((wave * 32 + r) * 1024);
; #pragma unroll
;         for (int mt = 0; mt < 2; ++mt)
; #pragma unroll
;             for (int g = 0; g < 4; ++g) { const int dv0 = 32 * mt + 8 * g + 4 * h; const f32x4 og = *(const f32x4*)(C.dog + l * 64 + dv0);
;                 v2u w; w.x = pkbf(O[0][mt][4 * g] * rs * og.x, O[0][mt][4 * g + 1] * rs * og.y); w.y = pkbf(O[0][mt][4 * g + 2] * rs * og.z, O[0][mt][4 * g + 3] * rs * og.w);
;                 *(v2u*)(op + dv0) = w; }
	v_add_f32_e32 v2, v2, v3
	v_fmamk_f32 v2, v2, 0x3c800000, v162
	v_cmp_gt_f32_e32 vcc, s78, v2
	v_mul_f32_e32 v3, 0x4b800000, v2
	s_nop 0
	v_cndmask_b32_e32 v2, v2, v3, vcc
	v_rsq_f32_e32 v2, v2
	s_nop 0
	v_mul_f32_e32 v3, 0x45800000, v2
	v_cndmask_b32_e32 v2, v2, v3, vcc
	v_mul_f32_e32 v10, v221, v2
	v_pk_mul_f32 v[2:3], v[48:49], v[10:11] op_sel_hi:[1,0]
	v_pk_mul_f32 v[4:5], v[18:19], v[10:11] op_sel_hi:[1,0]
	s_waitcnt vmcnt(0)
	v_pk_mul_f32 v[2:3], v[44:45], v[2:3]
	v_pk_mul_f32 v[4:5], v[46:47], v[4:5]
	v_cvt_pk_bf16_f32 v2, v2, v3
	v_cvt_pk_bf16_f32 v3, v4, v5
	v_add_co_u32_e32 v4, vcc, s4, v72
	v_pk_mul_f32 v[18:19], v[20:21], v[10:11] op_sel_hi:[1,0]
	s_nop 0
	v_addc_co_u32_e32 v5, vcc, 0, v73, vcc
	global_store_dwordx2 v[4:5], v[2:3], off offset:1536
	v_mov_b32_e32 v2, v164
	v_mov_b32_e32 v3, v165
	v_mov_b32_e32 v4, v166
	v_mov_b32_e32 v5, v167
	v_pk_mul_f32 v[6:7], v[6:7], v[10:11] op_sel_hi:[1,0]
	v_pk_mul_f32 v[0:1], v[0:1], v[10:11] op_sel_hi:[1,0]
	s_nop 0
	v_pk_mul_f32 v[2:3], v[2:3], v[18:19]
	v_pk_mul_f32 v[18:19], v[22:23], v[10:11] op_sel_hi:[1,0]
	v_cvt_pk_bf16_f32 v2, v2, v3
	v_pk_mul_f32 v[4:5], v[4:5], v[18:19]
	v_pk_mul_f32 v[18:19], v[24:25], v[10:11] op_sel_hi:[1,0]
	v_cvt_pk_bf16_f32 v3, v4, v5
	global_store_dwordx2 v[16:17], v[2:3], off offset:16
	v_mov_b32_e32 v2, v168
	v_mov_b32_e32 v3, v169
	v_mov_b32_e32 v4, v170
	v_mov_b32_e32 v5, v171
	s_nop 0
	v_pk_mul_f32 v[2:3], v[2:3], v[18:19]
	v_pk_mul_f32 v[18:19], v[26:27], v[10:11] op_sel_hi:[1,0]
	v_cvt_pk_bf16_f32 v2, v2, v3
	v_pk_mul_f32 v[4:5], v[4:5], v[18:19]
	v_pk_mul_f32 v[18:19], v[28:29], v[10:11] op_sel_hi:[1,0]
	v_cvt_pk_bf16_f32 v3, v4, v5
	global_store_dwordx2 v[16:17], v[2:3], off offset:32
	v_mov_b32_e32 v2, v172
	v_mov_b32_e32 v3, v173
	v_mov_b32_e32 v4, v174
	v_mov_b32_e32 v5, v175
	s_nop 0
	v_pk_mul_f32 v[2:3], v[2:3], v[18:19]
	v_pk_mul_f32 v[18:19], v[30:31], v[10:11] op_sel_hi:[1,0]
	v_cvt_pk_bf16_f32 v2, v2, v3
	v_pk_mul_f32 v[4:5], v[4:5], v[18:19]
	v_pk_mul_f32 v[18:19], v[32:33], v[10:11] op_sel_hi:[1,0]
	v_cvt_pk_bf16_f32 v3, v4, v5
	global_store_dwordx2 v[16:17], v[2:3], off offset:48
	v_mov_b32_e32 v2, v176
	v_mov_b32_e32 v3, v177
	v_mov_b32_e32 v4, v178
	v_mov_b32_e32 v5, v179
	s_nop 0
	v_pk_mul_f32 v[2:3], v[2:3], v[18:19]
	v_pk_mul_f32 v[18:19], v[34:35], v[10:11] op_sel_hi:[1,0]
	v_cvt_pk_bf16_f32 v2, v2, v3
	v_pk_mul_f32 v[4:5], v[4:5], v[18:19]
	v_pk_mul_f32 v[18:19], v[36:37], v[10:11] op_sel_hi:[1,0]
	v_cvt_pk_bf16_f32 v3, v4, v5
	global_store_dwordx2 v[16:17], v[2:3], off offset:64
	v_mov_b32_e32 v2, v180
	v_mov_b32_e32 v3, v181
	v_mov_b32_e32 v4, v182
	v_mov_b32_e32 v5, v183
	s_nop 0
	v_pk_mul_f32 v[2:3], v[2:3], v[18:19]
	v_pk_mul_f32 v[4:5], v[4:5], v[6:7]
	v_cvt_pk_bf16_f32 v2, v2, v3
	v_cvt_pk_bf16_f32 v3, v4, v5
	global_store_dwordx2 v[16:17], v[2:3], off offset:80
	v_mov_b32_e32 v2, v184
	v_mov_b32_e32 v3, v185
	v_mov_b32_e32 v4, v186
	v_mov_b32_e32 v5, v187
	v_pk_mul_f32 v[6:7], v[8:9], v[10:11] op_sel_hi:[1,0]
	s_nop 0
	v_pk_mul_f32 v[0:1], v[4:5], v[0:1]
	v_pk_mul_f32 v[2:3], v[2:3], v[6:7]
	v_pk_mul_f32 v[4:5], v[12:13], v[10:11] op_sel_hi:[1,0]
	v_cvt_pk_bf16_f32 v2, v2, v3
	v_cvt_pk_bf16_f32 v3, v0, v1
	global_store_dwordx2 v[16:17], v[2:3], off offset:96
	v_mov_b32_e32 v0, v188
	v_mov_b32_e32 v1, v189
	v_mov_b32_e32 v2, v190
	v_mov_b32_e32 v3, v191
	s_nop 0
	v_pk_mul_f32 v[0:1], v[0:1], v[4:5]
	v_pk_mul_f32 v[4:5], v[14:15], v[10:11] op_sel_hi:[1,0]
	v_cvt_pk_bf16_f32 v0, v0, v1
	v_pk_mul_f32 v[2:3], v[2:3], v[4:5]
	s_nop 0
	v_cvt_pk_bf16_f32 v1, v2, v3
	global_store_dwordx2 v[16:17], v[0:1], off offset:112
	s_cbranch_scc0 .LBB0_401
